# down-GEMM epilogue: per-row-group rs2 loads issued with the h loads (no wait after stores); on top of merge-epilogue load batching and attention Y-phase rewrite
# speedup vs baseline: 1.0166x; 1.0009x over previous
; DI void unpack8(u32x4 w, float* f) { f[0] = bflo(w.x); f[1] = bfhi(w.x); f[2] = bflo(w.y); f[3] = bfhi(w.y); f[4] = bflo(w.z); f[5] = bfhi(w.z); f[6] = bflo(w.w); f[7] = bfhi(w.w); }
;     DI void operator()(AccRef acc, const Unit& u, int wr, int wc, int fr, int fq) const {
;         const int col0 = u.pn * 256 + wc * 32 + 8 * fq;
;         const int row0 = u.pm * 256 + wr * 64 + fr;
; #pragma unroll
;         for (int ai = 0; ai < 2; ++ai) {
;             u32x4 hv[4][2];
; #pragma unroll
;             for (int m = 0; m < 4; ++m)
; #pragma unroll
;                 for (int bj = 0; bj < 2; ++bj) hv[m][bj] = __builtin_nontemporal_load((const u32x4*)(H16 + (size_t)(row0 + ai * 128 + m * 16) * 2048 + col0 + bj * 128));
; #pragma unroll
;             for (int m = 0; m < 4; ++m) { float* orow = out + (size_t)(row0 + ai * 128 + m * 16) * 2048; const float r2 = rs2[row0 + ai * 128 + m * 16];
; #pragma unroll
;                 for (int bj = 0; bj < 2; ++bj) { float h[8]; unpack8(hv[m][bj], h); const int cc = col0 + bj * 128;
;                     *(pg8::f32x4*)(orow + cc) = (pg8::f32x4){h[0], h[1], h[2], h[3]} + acc[ai][bj][m][0] * r2;
;                     *(pg8::f32x4*)(orow + cc + 4) = (pg8::f32x4){h[4], h[5], h[6], h[7]} + acc[ai][bj][m][1] * r2; } }
;         }
;     }
.LBB0_1294:
	v_lshl_or_b32 v128, s55, 8, v173
	v_lshl_add_u32 v158, s24, 8, v171
	v_ashrrev_i32_e32 v129, 31, v128
	v_ashrrev_i32_e32 v159, 31, v158
	v_lshl_add_u64 v[156:157], v[128:129], 1, s[4:5]
	v_lshlrev_b64 v[130:131], 12, v[158:159]
	v_lshl_add_u64 v[130:131], v[156:157], 0, v[130:131]
	v_lshl_add_u64 v[154:155], v[158:159], 2, s[6:7]
	global_load_dwordx4 v[178:181], v[130:131], off nt
	global_load_dwordx4 v[182:185], v[130:131], off offset:256 nt
	global_load_dword v202, v[154:155], off
	global_load_dword v220, v[154:155], off offset:64
	global_load_dword v222, v[154:155], off offset:128
	global_load_dword v224, v[154:155], off offset:192
	v_or_b32_e32 v204, 16, v158
	v_or_b32_e32 v206, 32, v158
	v_or_b32_e32 v162, 48, v158
	v_ashrrev_i32_e32 v205, 31, v204
	v_ashrrev_i32_e32 v207, 31, v206
	v_ashrrev_i32_e32 v163, 31, v162
	v_lshlrev_b64 v[130:131], 13, v[158:159]
	v_lshlrev_b64 v[152:153], 2, v[128:129]
	v_lshlrev_b64 v[128:129], 12, v[204:205]
	v_lshlrev_b64 v[132:133], 12, v[206:207]
	v_lshlrev_b64 v[134:135], 12, v[162:163]
	v_lshl_add_u64 v[130:131], s[26:27], 0, v[130:131]
	v_lshl_add_u64 v[128:129], v[156:157], 0, v[128:129]
	v_lshl_add_u64 v[132:133], v[156:157], 0, v[132:133]
	v_lshl_add_u64 v[210:211], v[156:157], 0, v[134:135]
	v_lshl_add_u64 v[212:213], v[130:131], 0, v[152:153]
	global_load_dwordx4 v[186:189], v[128:129], off nt
	global_load_dwordx4 v[190:193], v[128:129], off offset:256 nt
	global_load_dwordx4 v[194:197], v[132:133], off nt
	global_load_dwordx4 v[198:201], v[132:133], off offset:256 nt
	s_nop 0
	global_load_dwordx4 v[132:135], v[210:211], off nt
	global_load_dwordx4 v[128:131], v[210:211], off offset:256 nt
	v_lshl_add_u64 v[208:209], v[204:205], 2, s[6:7]
	s_andn2_b64 vcc, exec, s[2:3]
	s_mov_b64 s[2:3], -1
	s_waitcnt vmcnt(0)
	v_lshlrev_b32_e32 v210, 16, v178
	v_and_b32_e32 v211, 0xffff0000, v178
	v_lshlrev_b32_e32 v178, 16, v179
	v_and_b32_e32 v179, 0xffff0000, v179
	v_lshlrev_b32_e32 v214, 16, v180
	v_and_b32_e32 v215, 0xffff0000, v180
	v_lshlrev_b32_e32 v180, 16, v181
	v_and_b32_e32 v181, 0xffff0000, v181
	v_lshlrev_b32_e32 v216, 16, v182
	v_and_b32_e32 v217, 0xffff0000, v182
	v_lshlrev_b32_e32 v182, 16, v183
	v_and_b32_e32 v183, 0xffff0000, v183
	v_lshlrev_b32_e32 v218, 16, v184
	v_and_b32_e32 v219, 0xffff0000, v184
	v_lshlrev_b32_e32 v184, 16, v185
	v_and_b32_e32 v185, 0xffff0000, v185
	v_pk_fma_f32 v[126:127], v[126:127], v[202:203], v[178:179] op_sel_hi:[1,0,1]
	v_pk_fma_f32 v[124:125], v[124:125], v[202:203], v[210:211] op_sel_hi:[1,0,1]
	v_pk_fma_f32 v[122:123], v[122:123], v[202:203], v[180:181] op_sel_hi:[1,0,1]
	v_pk_fma_f32 v[120:121], v[120:121], v[202:203], v[214:215] op_sel_hi:[1,0,1]
	v_pk_fma_f32 v[118:119], v[118:119], v[202:203], v[182:183] op_sel_hi:[1,0,1]
	v_pk_fma_f32 v[116:117], v[116:117], v[202:203], v[216:217] op_sel_hi:[1,0,1]
	v_pk_fma_f32 v[114:115], v[114:115], v[202:203], v[184:185] op_sel_hi:[1,0,1]
	v_pk_fma_f32 v[112:113], v[112:113], v[202:203], v[218:219] op_sel_hi:[1,0,1]
	global_store_dwordx4 v[212:213], v[124:127], off
	global_store_dwordx4 v[212:213], v[120:123], off offset:16
	global_store_dwordx4 v[212:213], v[116:119], off offset:512
	global_store_dwordx4 v[212:213], v[112:115], off offset:528
	s_nop 0
	v_lshlrev_b32_e32 v118, 16, v186
	v_lshlrev_b64 v[114:115], 13, v[204:205]
	v_lshl_add_u64 v[114:115], s[26:27], 0, v[114:115]
	v_and_b32_e32 v119, 0xffff0000, v186
	v_lshlrev_b32_e32 v120, 16, v187
	v_and_b32_e32 v121, 0xffff0000, v187
	v_lshl_add_u64 v[114:115], v[114:115], 0, v[152:153]
	v_lshlrev_b32_e32 v122, 16, v188
	v_and_b32_e32 v123, 0xffff0000, v188
	v_lshlrev_b32_e32 v124, 16, v189
	v_and_b32_e32 v125, 0xffff0000, v189
	v_lshlrev_b32_e32 v126, 16, v190
	v_and_b32_e32 v127, 0xffff0000, v190
	v_lshlrev_b32_e32 v178, 16, v191
	v_and_b32_e32 v179, 0xffff0000, v191
	v_lshlrev_b32_e32 v180, 16, v192
	v_and_b32_e32 v181, 0xffff0000, v192
	v_lshlrev_b32_e32 v182, 16, v193
	v_and_b32_e32 v183, 0xffff0000, v193
	v_lshl_add_u64 v[116:117], v[206:207], 2, s[6:7]
	v_pk_fma_f32 v[110:111], v[110:111], v[220:221], v[120:121] op_sel_hi:[1,0,1]
	v_pk_fma_f32 v[108:109], v[108:109], v[220:221], v[118:119] op_sel_hi:[1,0,1]
	v_pk_fma_f32 v[106:107], v[106:107], v[220:221], v[124:125] op_sel_hi:[1,0,1]
	v_pk_fma_f32 v[104:105], v[104:105], v[220:221], v[122:123] op_sel_hi:[1,0,1]
	v_pk_fma_f32 v[102:103], v[102:103], v[220:221], v[178:179] op_sel_hi:[1,0,1]
	v_pk_fma_f32 v[100:101], v[100:101], v[220:221], v[126:127] op_sel_hi:[1,0,1]
	v_pk_fma_f32 v[98:99], v[98:99], v[220:221], v[182:183] op_sel_hi:[1,0,1]
	v_pk_fma_f32 v[96:97], v[96:97], v[220:221], v[180:181] op_sel_hi:[1,0,1]
	global_store_dwordx4 v[114:115], v[108:111], off
	global_store_dwordx4 v[114:115], v[104:107], off offset:16
	global_store_dwordx4 v[114:115], v[100:103], off offset:512
	global_store_dwordx4 v[114:115], v[96:99], off offset:528
	s_nop 0
	v_lshlrev_b32_e32 v102, 16, v194
	v_lshlrev_b64 v[98:99], 13, v[206:207]
	v_lshl_add_u64 v[98:99], s[26:27], 0, v[98:99]
	v_and_b32_e32 v103, 0xffff0000, v194
	v_lshlrev_b32_e32 v104, 16, v195
	v_and_b32_e32 v105, 0xffff0000, v195
	v_lshl_add_u64 v[98:99], v[98:99], 0, v[152:153]
	v_lshlrev_b32_e32 v106, 16, v196
	v_and_b32_e32 v107, 0xffff0000, v196
	v_lshlrev_b32_e32 v108, 16, v197
	v_and_b32_e32 v109, 0xffff0000, v197
	v_lshlrev_b32_e32 v110, 16, v198
	v_and_b32_e32 v111, 0xffff0000, v198
	v_lshlrev_b32_e32 v112, 16, v199
	v_and_b32_e32 v113, 0xffff0000, v199
	v_lshlrev_b32_e32 v114, 16, v200
	v_and_b32_e32 v115, 0xffff0000, v200
	v_lshlrev_b32_e32 v116, 16, v201
	v_and_b32_e32 v117, 0xffff0000, v201
	v_lshl_add_u64 v[100:101], v[162:163], 2, s[6:7]
; DI void unpack8(u32x4 w, float* f) { f[0] = bflo(w.x); f[1] = bfhi(w.x); f[2] = bflo(w.y); f[3] = bfhi(w.y); f[4] = bflo(w.z); f[5] = bfhi(w.z); f[6] = bflo(w.w); f[7] = bfhi(w.w); }
;     DI void operator()(AccRef acc, const Unit& u, int wr, int wc, int fr, int fq) const {
;         const int col0 = u.pn * 256 + wc * 32 + 8 * fq;
;         const int row0 = u.pm * 256 + wr * 64 + fr;
; #pragma unroll
;         for (int ai = 0; ai < 2; ++ai) {
;             u32x4 hv[4][2];
; #pragma unroll
;             for (int m = 0; m < 4; ++m)
; #pragma unroll
;                 for (int bj = 0; bj < 2; ++bj) hv[m][bj] = __builtin_nontemporal_load((const u32x4*)(H16 + (size_t)(row0 + ai * 128 + m * 16) * 2048 + col0 + bj * 128));
; #pragma unroll
;             for (int m = 0; m < 4; ++m) { float* orow = out + (size_t)(row0 + ai * 128 + m * 16) * 2048; const float r2 = rs2[row0 + ai * 128 + m * 16];
; #pragma unroll
;                 for (int bj = 0; bj < 2; ++bj) { float h[8]; unpack8(hv[m][bj], h); const int cc = col0 + bj * 128;
;                     *(pg8::f32x4*)(orow + cc) = (pg8::f32x4){h[0], h[1], h[2], h[3]} + acc[ai][bj][m][0] * r2;
;                     *(pg8::f32x4*)(orow + cc + 4) = (pg8::f32x4){h[4], h[5], h[6], h[7]} + acc[ai][bj][m][1] * r2; } }
;         }
;     }
	v_pk_fma_f32 v[94:95], v[94:95], v[222:223], v[104:105] op_sel_hi:[1,0,1]
	v_pk_fma_f32 v[92:93], v[92:93], v[222:223], v[102:103] op_sel_hi:[1,0,1]
	v_pk_fma_f32 v[90:91], v[90:91], v[222:223], v[108:109] op_sel_hi:[1,0,1]
	v_pk_fma_f32 v[88:89], v[88:89], v[222:223], v[106:107] op_sel_hi:[1,0,1]
	v_pk_fma_f32 v[86:87], v[86:87], v[222:223], v[112:113] op_sel_hi:[1,0,1]
	v_pk_fma_f32 v[84:85], v[84:85], v[222:223], v[110:111] op_sel_hi:[1,0,1]
	v_pk_fma_f32 v[82:83], v[82:83], v[222:223], v[116:117] op_sel_hi:[1,0,1]
	v_pk_fma_f32 v[80:81], v[80:81], v[222:223], v[114:115] op_sel_hi:[1,0,1]
	global_store_dwordx4 v[98:99], v[92:95], off
	global_store_dwordx4 v[98:99], v[88:91], off offset:16
	global_store_dwordx4 v[98:99], v[84:87], off offset:512
	global_store_dwordx4 v[98:99], v[80:83], off offset:528
	s_nop 0
	v_lshlrev_b64 v[84:85], 13, v[162:163]
	v_add_u32_e32 v82, 0x80, v158
	v_ashrrev_i32_e32 v83, 31, v82
	v_lshl_add_u64 v[84:85], s[26:27], 0, v[84:85]
	v_lshlrev_b32_e32 v88, 16, v132
	v_and_b32_e32 v89, 0xffff0000, v132
	v_lshlrev_b32_e32 v90, 16, v133
	v_and_b32_e32 v91, 0xffff0000, v133
	v_lshlrev_b64 v[86:87], 12, v[82:83]
	v_lshl_add_u64 v[84:85], v[84:85], 0, v[152:153]
	v_lshlrev_b32_e32 v92, 16, v134
	v_and_b32_e32 v93, 0xffff0000, v134
	v_lshlrev_b32_e32 v94, 16, v135
	v_and_b32_e32 v95, 0xffff0000, v135
	v_lshlrev_b32_e32 v96, 16, v128
	v_and_b32_e32 v97, 0xffff0000, v128
	v_lshlrev_b32_e32 v98, 16, v129
	v_and_b32_e32 v99, 0xffff0000, v129
	v_lshlrev_b32_e32 v100, 16, v130
	v_and_b32_e32 v101, 0xffff0000, v130
	v_lshlrev_b32_e32 v102, 16, v131
	v_and_b32_e32 v103, 0xffff0000, v131
	v_lshl_add_u64 v[86:87], v[156:157], 0, v[86:87]
	v_pk_fma_f32 v[78:79], v[78:79], v[224:225], v[90:91] op_sel_hi:[1,0,1]
	v_pk_fma_f32 v[76:77], v[76:77], v[224:225], v[88:89] op_sel_hi:[1,0,1]
	v_pk_fma_f32 v[74:75], v[74:75], v[224:225], v[94:95] op_sel_hi:[1,0,1]
	v_pk_fma_f32 v[72:73], v[72:73], v[224:225], v[92:93] op_sel_hi:[1,0,1]
	v_pk_fma_f32 v[70:71], v[70:71], v[224:225], v[98:99] op_sel_hi:[1,0,1]
	v_pk_fma_f32 v[68:69], v[68:69], v[224:225], v[96:97] op_sel_hi:[1,0,1]
	v_pk_fma_f32 v[66:67], v[66:67], v[224:225], v[102:103] op_sel_hi:[1,0,1]
	v_pk_fma_f32 v[64:65], v[64:65], v[224:225], v[100:101] op_sel_hi:[1,0,1]
	global_store_dwordx4 v[84:85], v[76:79], off
	global_store_dwordx4 v[84:85], v[72:75], off offset:16
	global_store_dwordx4 v[84:85], v[68:71], off offset:512
	global_store_dwordx4 v[84:85], v[64:67], off offset:528
	global_load_dwordx4 v[74:77], v[86:87], off nt
	s_nop 0
	global_load_dwordx4 v[78:81], v[86:87], off offset:256 nt
	global_load_dword v98, v[154:155], off offset:512
	global_load_dword v220, v[154:155], off offset:576
	global_load_dword v222, v[154:155], off offset:640
	global_load_dword v224, v[154:155], off offset:704
	v_add_u32_e32 v100, 0x90, v158
	v_add_u32_e32 v102, 0xa0, v158
	v_add_u32_e32 v72, 0xb0, v158
	v_ashrrev_i32_e32 v101, 31, v100
	v_ashrrev_i32_e32 v103, 31, v102
	v_ashrrev_i32_e32 v73, 31, v72
	v_lshlrev_b64 v[64:65], 12, v[100:101]
	v_lshlrev_b64 v[66:67], 12, v[102:103]
	v_lshlrev_b64 v[68:69], 12, v[72:73]
	v_lshlrev_b64 v[70:71], 13, v[82:83]
	v_lshl_add_u64 v[64:65], v[156:157], 0, v[64:65]
	v_lshl_add_u64 v[66:67], v[156:157], 0, v[66:67]
	v_lshl_add_u64 v[104:105], v[156:157], 0, v[68:69]
	v_lshl_add_u64 v[68:69], s[26:27], 0, v[70:71]
	v_lshl_add_u64 v[106:107], v[68:69], 0, v[152:153]
	global_load_dwordx4 v[82:85], v[64:65], off nt
	global_load_dwordx4 v[86:89], v[64:65], off offset:256 nt
	global_load_dwordx4 v[90:93], v[66:67], off nt
	global_load_dwordx4 v[94:97], v[66:67], off offset:256 nt
	global_load_dwordx4 v[68:71], v[104:105], off nt
	s_nop 0
	global_load_dwordx4 v[64:67], v[104:105], off offset:256 nt
	s_waitcnt vmcnt(11)
	v_lshlrev_b32_e32 v104, 16, v74
	v_and_b32_e32 v105, 0xffff0000, v74
	v_lshlrev_b32_e32 v74, 16, v75
	v_and_b32_e32 v75, 0xffff0000, v75
	v_lshlrev_b32_e32 v108, 16, v76
	v_and_b32_e32 v109, 0xffff0000, v76
	v_lshlrev_b32_e32 v76, 16, v77
	v_and_b32_e32 v77, 0xffff0000, v77
	s_waitcnt vmcnt(10)
	v_lshlrev_b32_e32 v110, 16, v78
	v_and_b32_e32 v111, 0xffff0000, v78
	v_lshlrev_b32_e32 v78, 16, v79
	v_and_b32_e32 v79, 0xffff0000, v79
	v_lshlrev_b32_e32 v112, 16, v80
	v_and_b32_e32 v113, 0xffff0000, v80
	v_lshlrev_b32_e32 v80, 16, v81
	v_and_b32_e32 v81, 0xffff0000, v81
	s_waitcnt vmcnt(9)
	v_pk_fma_f32 v[62:63], v[62:63], v[98:99], v[74:75] op_sel_hi:[1,0,1]
	v_pk_fma_f32 v[60:61], v[60:61], v[98:99], v[104:105] op_sel_hi:[1,0,1]
	v_pk_fma_f32 v[58:59], v[58:59], v[98:99], v[76:77] op_sel_hi:[1,0,1]
	v_pk_fma_f32 v[56:57], v[56:57], v[98:99], v[108:109] op_sel_hi:[1,0,1]
	v_pk_fma_f32 v[54:55], v[54:55], v[98:99], v[78:79] op_sel_hi:[1,0,1]
	v_pk_fma_f32 v[52:53], v[52:53], v[98:99], v[110:111] op_sel_hi:[1,0,1]
	v_pk_fma_f32 v[50:51], v[50:51], v[98:99], v[80:81] op_sel_hi:[1,0,1]
	v_pk_fma_f32 v[48:49], v[48:49], v[98:99], v[112:113] op_sel_hi:[1,0,1]
	global_store_dwordx4 v[106:107], v[60:63], off
	global_store_dwordx4 v[106:107], v[56:59], off offset:16
	global_store_dwordx4 v[106:107], v[52:55], off offset:512
	global_store_dwordx4 v[106:107], v[48:51], off offset:528
	s_nop 0
	s_waitcnt vmcnt(9)
; DI void unpack8(u32x4 w, float* f) { f[0] = bflo(w.x); f[1] = bfhi(w.x); f[2] = bflo(w.y); f[3] = bfhi(w.y); f[4] = bflo(w.z); f[5] = bfhi(w.z); f[6] = bflo(w.w); f[7] = bfhi(w.w); }
;     DI void operator()(AccRef acc, const Unit& u, int wr, int wc, int fr, int fq) const {
;     ...
;                 for (int bj = 0; bj < 2; ++bj) hv[m][bj] = __builtin_nontemporal_load((const u32x4*)(H16 + (size_t)(row0 + ai * 128 + m * 16) * 2048 + col0 + bj * 128));
; #pragma unroll
;             for (int m = 0; m < 4; ++m) { float* orow = out + (size_t)(row0 + ai * 128 + m * 16) * 2048; const float r2 = rs2[row0 + ai * 128 + m * 16];
; #pragma unroll
;                 for (int bj = 0; bj < 2; ++bj) { float h[8]; unpack8(hv[m][bj], h); const int cc = col0 + bj * 128;
;                     *(pg8::f32x4*)(orow + cc) = (pg8::f32x4){h[0], h[1], h[2], h[3]} + acc[ai][bj][m][0] * r2;
;                     *(pg8::f32x4*)(orow + cc + 4) = (pg8::f32x4){h[4], h[5], h[6], h[7]} + acc[ai][bj][m][1] * r2; } }
	v_lshlrev_b32_e32 v52, 16, v82
	v_lshlrev_b64 v[50:51], 13, v[100:101]
	v_lshl_add_u64 v[50:51], s[26:27], 0, v[50:51]
	v_and_b32_e32 v53, 0xffff0000, v82
	v_lshlrev_b32_e32 v54, 16, v83
	v_and_b32_e32 v55, 0xffff0000, v83
	v_lshl_add_u64 v[50:51], v[50:51], 0, v[152:153]
	v_lshlrev_b32_e32 v56, 16, v84
	v_and_b32_e32 v57, 0xffff0000, v84
	v_lshlrev_b32_e32 v58, 16, v85
	v_and_b32_e32 v59, 0xffff0000, v85
	s_waitcnt vmcnt(8)
	v_lshlrev_b32_e32 v60, 16, v86
	v_and_b32_e32 v61, 0xffff0000, v86
	v_lshlrev_b32_e32 v62, 16, v87
	v_and_b32_e32 v63, 0xffff0000, v87
	v_lshlrev_b32_e32 v74, 16, v88
	v_and_b32_e32 v75, 0xffff0000, v88
	v_lshlrev_b32_e32 v76, 16, v89
	v_and_b32_e32 v77, 0xffff0000, v89
	s_waitcnt vmcnt(4)
	v_pk_fma_f32 v[46:47], v[46:47], v[220:221], v[54:55] op_sel_hi:[1,0,1]
	v_pk_fma_f32 v[44:45], v[44:45], v[220:221], v[52:53] op_sel_hi:[1,0,1]
	v_pk_fma_f32 v[42:43], v[42:43], v[220:221], v[58:59] op_sel_hi:[1,0,1]
	v_pk_fma_f32 v[40:41], v[40:41], v[220:221], v[56:57] op_sel_hi:[1,0,1]
	v_pk_fma_f32 v[38:39], v[38:39], v[220:221], v[62:63] op_sel_hi:[1,0,1]
	v_pk_fma_f32 v[36:37], v[36:37], v[220:221], v[60:61] op_sel_hi:[1,0,1]
	v_pk_fma_f32 v[34:35], v[34:35], v[220:221], v[76:77] op_sel_hi:[1,0,1]
	v_pk_fma_f32 v[32:33], v[32:33], v[220:221], v[74:75] op_sel_hi:[1,0,1]
	global_store_dwordx4 v[50:51], v[44:47], off
	global_store_dwordx4 v[50:51], v[40:43], off offset:16
	global_store_dwordx4 v[50:51], v[36:39], off offset:512
	global_store_dwordx4 v[50:51], v[32:35], off offset:528
	s_nop 0
	v_lshlrev_b32_e32 v36, 16, v90
	v_lshlrev_b64 v[34:35], 13, v[102:103]
	v_lshl_add_u64 v[34:35], s[26:27], 0, v[34:35]
	v_and_b32_e32 v37, 0xffff0000, v90
	v_lshlrev_b32_e32 v38, 16, v91
	v_and_b32_e32 v39, 0xffff0000, v91
	v_lshl_add_u64 v[34:35], v[34:35], 0, v[152:153]
	v_lshlrev_b32_e32 v40, 16, v92
	v_and_b32_e32 v41, 0xffff0000, v92
	v_lshlrev_b32_e32 v42, 16, v93
	v_and_b32_e32 v43, 0xffff0000, v93
	v_lshlrev_b32_e32 v44, 16, v94
	v_and_b32_e32 v45, 0xffff0000, v94
	v_lshlrev_b32_e32 v46, 16, v95
	v_and_b32_e32 v47, 0xffff0000, v95
	v_lshlrev_b32_e32 v48, 16, v96
	v_and_b32_e32 v49, 0xffff0000, v96
	v_lshlrev_b32_e32 v50, 16, v97
	v_and_b32_e32 v51, 0xffff0000, v97
	v_pk_fma_f32 v[30:31], v[30:31], v[222:223], v[38:39] op_sel_hi:[1,0,1]
	v_pk_fma_f32 v[28:29], v[28:29], v[222:223], v[36:37] op_sel_hi:[1,0,1]
	v_pk_fma_f32 v[26:27], v[26:27], v[222:223], v[42:43] op_sel_hi:[1,0,1]
	v_pk_fma_f32 v[24:25], v[24:25], v[222:223], v[40:41] op_sel_hi:[1,0,1]
	v_pk_fma_f32 v[22:23], v[22:23], v[222:223], v[46:47] op_sel_hi:[1,0,1]
	v_pk_fma_f32 v[20:21], v[20:21], v[222:223], v[44:45] op_sel_hi:[1,0,1]
	v_pk_fma_f32 v[18:19], v[18:19], v[222:223], v[50:51] op_sel_hi:[1,0,1]
	v_pk_fma_f32 v[16:17], v[16:17], v[222:223], v[48:49] op_sel_hi:[1,0,1]
	global_store_dwordx4 v[34:35], v[28:31], off
	global_store_dwordx4 v[34:35], v[24:27], off offset:16
	global_store_dwordx4 v[34:35], v[20:23], off offset:512
	global_store_dwordx4 v[34:35], v[16:19], off offset:528
	s_nop 0
	v_lshlrev_b32_e32 v20, 16, v68
	v_lshlrev_b64 v[18:19], 13, v[72:73]
	v_lshl_add_u64 v[18:19], s[26:27], 0, v[18:19]
	v_and_b32_e32 v21, 0xffff0000, v68
	v_lshlrev_b32_e32 v22, 16, v69
	v_and_b32_e32 v23, 0xffff0000, v69
	v_lshl_add_u64 v[18:19], v[18:19], 0, v[152:153]
	v_lshlrev_b32_e32 v24, 16, v70
	v_and_b32_e32 v25, 0xffff0000, v70
	v_lshlrev_b32_e32 v26, 16, v71
	v_and_b32_e32 v27, 0xffff0000, v71
	v_lshlrev_b32_e32 v28, 16, v64
	v_and_b32_e32 v29, 0xffff0000, v64
	v_lshlrev_b32_e32 v30, 16, v65
	v_and_b32_e32 v31, 0xffff0000, v65
	v_lshlrev_b32_e32 v32, 16, v66
	v_and_b32_e32 v33, 0xffff0000, v66
	v_lshlrev_b32_e32 v34, 16, v67
	v_and_b32_e32 v35, 0xffff0000, v67
	v_pk_fma_f32 v[14:15], v[14:15], v[224:225], v[22:23] op_sel_hi:[1,0,1]
	v_pk_fma_f32 v[12:13], v[12:13], v[224:225], v[20:21] op_sel_hi:[1,0,1]
	v_pk_fma_f32 v[10:11], v[10:11], v[224:225], v[26:27] op_sel_hi:[1,0,1]
	v_pk_fma_f32 v[8:9], v[8:9], v[224:225], v[24:25] op_sel_hi:[1,0,1]
	v_pk_fma_f32 v[6:7], v[6:7], v[224:225], v[30:31] op_sel_hi:[1,0,1]
	v_pk_fma_f32 v[4:5], v[4:5], v[224:225], v[28:29] op_sel_hi:[1,0,1]
	v_pk_fma_f32 v[2:3], v[2:3], v[224:225], v[34:35] op_sel_hi:[1,0,1]
	v_pk_fma_f32 v[0:1], v[0:1], v[224:225], v[32:33] op_sel_hi:[1,0,1]
	global_store_dwordx4 v[18:19], v[12:15], off
	global_store_dwordx4 v[18:19], v[8:11], off offset:16
	global_store_dwordx4 v[18:19], v[4:7], off offset:512
	global_store_dwordx4 v[18:19], v[0:3], off offset:528
	s_cbranch_vccnz .LBB0_1283
	s_andn2_b64 vcc, exec, s[0:1]
	s_cbranch_vccnz .LBB0_1282
	s_barrier
	s_branch .LBB0_1282
